# cache policy: final RMSNorm out stores as device-scope write-through (sc1 nt) so the end-of-kernel L2 write-back has less to flush; on top of v031
# speedup vs baseline: 1.0137x; 1.0005x over previous
; __device__ __forceinline__ void final_phase(float* x, const float* ssq, const float* gn, bool team) {
;     ...
;     for (int m = mbeg; m < mend; m += mstep) { float s = ssq[(size_t)m * 32 + (lane & 31)];
; #pragma unroll
;         for (int o = 1; o < 32; o <<= 1) s += __shfl_xor(s, o);
;         const float rs = __builtin_amdgcn_rsqf(s * (1.0f / D) + 1e-6f); f32x4* xr = (f32x4*)(x + (size_t)m * D) + lane; const f32x4* gr = (const f32x4*)gn + lane;
; #pragma unroll
;         for (int j = 0; j < 8; ++j) xr[64 * j] = xr[64 * j] * rs * gr[64 * j]; }
.LBB0_2364:
	global_load_dword v3, v[18:19], off
	global_load_dwordx4 v[76:79], v[14:15], off offset:-4096
	global_load_dwordx4 v[80:83], v[14:15], off offset:-3072
	global_load_dwordx4 v[84:87], v[14:15], off offset:-2048
	global_load_dwordx4 v[88:91], v[14:15], off offset:-1024
	global_load_dwordx4 v[92:95], v[14:15], off
	global_load_dwordx4 v[96:99], v[14:15], off offset:1024
	global_load_dwordx4 v[100:103], v[14:15], off offset:2048
	global_load_dwordx4 v[104:107], v[14:15], off offset:3072
	v_add_u32_e32 v0, v0, v2
	v_cmp_ge_i32_e32 vcc, v0, v22
	v_lshl_add_u64 v[18:19], v[18:19], 0, v[20:21]
	s_or_b64 s[0:1], vcc, s[0:1]
	s_waitcnt vmcnt(8)
	ds_bpermute_b32 v40, v23, v3
	s_waitcnt lgkmcnt(0)
	v_add_f32_e32 v3, v3, v40
	ds_bpermute_b32 v40, v24, v3
	s_waitcnt lgkmcnt(0)
	v_add_f32_e32 v3, v3, v40
	ds_bpermute_b32 v40, v25, v3
	s_waitcnt lgkmcnt(0)
	v_add_f32_e32 v3, v3, v40
	ds_bpermute_b32 v40, v26, v3
	s_waitcnt lgkmcnt(0)
	v_add_f32_e32 v3, v3, v40
	ds_bpermute_b32 v40, v27, v3
	s_waitcnt lgkmcnt(0)
	v_add_f32_e32 v3, v3, v40
	v_fmamk_f32 v3, v3, 0x3a000000, v1
	v_rsq_f32_e32 v40, v3
	s_waitcnt vmcnt(7)
	v_pk_mul_f32 v[76:77], v[76:77], v[40:41] op_sel_hi:[1,0]
	v_pk_mul_f32 v[78:79], v[78:79], v[40:41] op_sel_hi:[1,0]
	v_pk_mul_f32 v[76:77], v[44:45], v[76:77]
	v_pk_mul_f32 v[78:79], v[46:47], v[78:79]
	global_store_dwordx4 v[14:15], v[76:79], off offset:-4096 sc1 nt
	s_waitcnt vmcnt(7)
	v_pk_mul_f32 v[80:81], v[80:81], v[40:41] op_sel_hi:[1,0]
	v_pk_mul_f32 v[82:83], v[82:83], v[40:41] op_sel_hi:[1,0]
	v_pk_mul_f32 v[80:81], v[48:49], v[80:81]
	v_pk_mul_f32 v[82:83], v[50:51], v[82:83]
	global_store_dwordx4 v[14:15], v[80:83], off offset:-3072 sc1 nt
	s_waitcnt vmcnt(7)
	v_pk_mul_f32 v[84:85], v[84:85], v[40:41] op_sel_hi:[1,0]
	v_pk_mul_f32 v[86:87], v[86:87], v[40:41] op_sel_hi:[1,0]
	v_pk_mul_f32 v[84:85], v[52:53], v[84:85]
	v_pk_mul_f32 v[86:87], v[54:55], v[86:87]
	global_store_dwordx4 v[14:15], v[84:87], off offset:-2048 sc1 nt
	s_waitcnt vmcnt(7)
	v_pk_mul_f32 v[88:89], v[88:89], v[40:41] op_sel_hi:[1,0]
	v_pk_mul_f32 v[90:91], v[90:91], v[40:41] op_sel_hi:[1,0]
	v_pk_mul_f32 v[88:89], v[56:57], v[88:89]
	v_pk_mul_f32 v[90:91], v[58:59], v[90:91]
	global_store_dwordx4 v[14:15], v[88:91], off offset:-1024 sc1 nt
	s_waitcnt vmcnt(7)
	v_pk_mul_f32 v[92:93], v[92:93], v[40:41] op_sel_hi:[1,0]
	v_pk_mul_f32 v[94:95], v[94:95], v[40:41] op_sel_hi:[1,0]
	v_pk_mul_f32 v[92:93], v[60:61], v[92:93]
	v_pk_mul_f32 v[94:95], v[62:63], v[94:95]
	global_store_dwordx4 v[14:15], v[92:95], off sc1 nt
	s_waitcnt vmcnt(7)
	v_pk_mul_f32 v[96:97], v[96:97], v[40:41] op_sel_hi:[1,0]
	v_pk_mul_f32 v[98:99], v[98:99], v[40:41] op_sel_hi:[1,0]
	v_pk_mul_f32 v[96:97], v[64:65], v[96:97]
	v_pk_mul_f32 v[98:99], v[66:67], v[98:99]
	global_store_dwordx4 v[14:15], v[96:99], off offset:1024 sc1 nt
	s_waitcnt vmcnt(7)
	v_pk_mul_f32 v[100:101], v[100:101], v[40:41] op_sel_hi:[1,0]
	v_pk_mul_f32 v[102:103], v[102:103], v[40:41] op_sel_hi:[1,0]
	v_pk_mul_f32 v[100:101], v[68:69], v[100:101]
	v_pk_mul_f32 v[102:103], v[70:71], v[102:103]
	global_store_dwordx4 v[14:15], v[100:103], off offset:2048 sc1 nt
	s_waitcnt vmcnt(7)
	v_pk_mul_f32 v[104:105], v[104:105], v[40:41] op_sel_hi:[1,0]
	v_pk_mul_f32 v[106:107], v[106:107], v[40:41] op_sel_hi:[1,0]
	v_pk_mul_f32 v[104:105], v[72:73], v[104:105]
	v_pk_mul_f32 v[106:107], v[74:75], v[106:107]
	global_store_dwordx4 v[14:15], v[104:107], off offset:3072 sc1 nt
	v_lshl_add_u64 v[14:15], v[14:15], 0, v[16:17]
	s_andn2_b64 exec, exec, s[0:1]
	s_cbranch_execnz .LBB0_2364
